# diff attention second tile: next PV step's exp/cvt interleaved into the gaps between the current step's 4 PV MFMAs (P double-buffered in v[86:89]/v[218:221]) instead of a VALU block before the MFMA gr
# baseline (speedup 1.0000x reference)
; #define LAS __attribute__((address_space(3)))
; #define MFMA32(a, b, c) __builtin_amdgcn_mfma_f32_32x32x16_bf16((a), (b), (c), 0, 0, 0)
; DI void qk_scores(const LAS uchar* Kb, int kc0, const bf16x8 (&qf)[4], f32x16 (&S)[2], int r, int hh) {
;     const int ksw = r & 15; const LAS uchar* kp = Kb + r * 256;
; #pragma unroll
;     for (int kb = 0; kb < 2; ++kb) {
;         bf16x8 kf[4];
; #pragma unroll
;         for (int s = 0; s < 4; ++s) kf[s] = *(const LAS bf16x8*)(kp + kb * 32 * 256 + (((kc0 + 2 * s + hh) ^ ksw) * 16));
;         { const f32x16 zero16 = {0.f, 0.f, 0.f, 0.f, 0.f, 0.f, 0.f, 0.f, 0.f, 0.f, 0.f, 0.f, 0.f, 0.f, 0.f, 0.f}; S[kb] = MFMA32(kf[0], qf[0], zero16); }
; #pragma unroll
;         for (int s = 1; s < 4; ++s) S[kb] = MFMA32(kf[s], qf[s], S[kb]);
;     }
; }
; template <bool HASNEXT>
; DI void attn_tile_pipe(const LAS uchar* Kn, int kc0, const LAS uchar* Vb, const bf16x8 (&qf)[4], f32x16 (&O)[4], f32x16 (&S)[2], f32x16 (&Sn)[2], float& m, float& l, int r, int hh, bool force) {
;     ...
;     if (HASNEXT) {
;         __builtin_amdgcn_sched_barrier(0);
;         Sn[0] = MFMA32(kf[0], qf[0], zero16);
; #pragma unroll
;         for (int s = 1; s < 4; ++s) Sn[0] = MFMA32(kf[s], qf[s], Sn[0]);
;         __builtin_amdgcn_sched_barrier(0);
; #pragma unroll
;         for (int s = 0; s < 4; ++s) kf[s] = *(const LAS bf16x8*)(kp + 32 * 256 + (((kc0 + 2 * s + hh) ^ ksw) * 16));
;         __builtin_amdgcn_sched_barrier(0);
;     }
;     ATT_P(0);
;     if (HASNEXT) {
;         __builtin_amdgcn_sched_barrier(0);
;         Sn[1] = MFMA32(kf[0], qf[0], zero16);
; #pragma unroll
;         for (int s = 1; s < 4; ++s) Sn[1] = MFMA32(kf[s], qf[s], Sn[1]);
;     }
; #pragma unroll
;     for (int step = 0; step < 4; ++step) {
;         const bf16x8 pf = __builtin_bit_cast(bf16x8, pw);
;         __builtin_amdgcn_sched_barrier(0);
; #pragma unroll
;         for (int d = 0; d < DVB; ++d) O[d] = MFMA32(vf[d], pf, O[d]);
;         __builtin_amdgcn_sched_barrier(0);
;         if (step < 3) {
; #pragma unroll
;             for (int d = 0; d < DVB; ++d) vf[d] = *(const LAS bf16x8*)(vp + d * 32 * 128 + (((2 * (step + 1) + hh) ^ vsw) * 16));
;             __builtin_amdgcn_sched_barrier(0);
;             ATT_P(step + 1);
;         }
;     }
;     ...
;     l += la0;
.LBB0_2027:
	v_exp_f32_e32 v114, v114
	v_exp_f32_e32 v115, v115
	v_exp_f32_e32 v116, v116
	v_exp_f32_e32 v117, v117
	v_exp_f32_e32 v118, v118
	v_exp_f32_e32 v119, v119
	v_exp_f32_e32 v120, v120
	v_exp_f32_e32 v121, v121
	v_cvt_pk_bf16_f32 v86, v114, v115
	v_cvt_pk_bf16_f32 v87, v116, v117
	v_cvt_pk_bf16_f32 v88, v118, v119
	v_cvt_pk_bf16_f32 v89, v120, v121
	s_waitcnt lgkmcnt(3)
	s_nop 0
	v_mfma_f32_32x32x16_bf16 v[50:65], v[78:81], v[86:89], v[50:65]
	ds_read_b128 v[78:81], v82 offset:49152
	v_exp_f32_e32 v122, v122
	v_exp_f32_e32 v123, v123
	v_exp_f32_e32 v124, v124
	s_waitcnt lgkmcnt(3)
	v_mfma_f32_32x32x16_bf16 v[34:49], v[74:77], v[86:89], v[34:49]
	ds_read_b128 v[74:77], v82 offset:53248
	v_cvt_pk_bf16_f32 v218, v122, v123
	v_exp_f32_e32 v125, v125
	v_exp_f32_e32 v126, v126
	s_waitcnt lgkmcnt(3)
	v_mfma_f32_32x32x16_bf16 v[18:33], v[70:73], v[86:89], v[18:33]
	ds_read_b128 v[70:73], v82 offset:57344
	v_exp_f32_e32 v127, v127
	v_cvt_pk_bf16_f32 v219, v124, v125
	v_exp_f32_e32 v128, v128
	s_waitcnt lgkmcnt(3)
	v_mfma_f32_32x32x16_bf16 v[2:17], v[66:69], v[86:89], v[2:17]
	ds_read_b128 v[66:69], v82 offset:61440
	v_exp_f32_e32 v129, v129
	v_cvt_pk_bf16_f32 v220, v126, v127
	v_cvt_pk_bf16_f32 v221, v128, v129
	s_waitcnt lgkmcnt(3)
	s_nop 0
	v_mfma_f32_32x32x16_bf16 v[50:65], v[78:81], v[218:221], v[50:65]
	ds_read_b128 v[78:81], v83 offset:49152
	v_exp_f32_e32 v147, v98
	v_exp_f32_e32 v148, v99
	v_exp_f32_e32 v149, v100
	s_waitcnt lgkmcnt(3)
	v_mfma_f32_32x32x16_bf16 v[34:49], v[74:77], v[218:221], v[34:49]
	ds_read_b128 v[74:77], v83 offset:53248
	v_cvt_pk_bf16_f32 v86, v147, v148
	v_exp_f32_e32 v150, v101
	v_exp_f32_e32 v151, v102
	s_waitcnt lgkmcnt(3)
	v_mfma_f32_32x32x16_bf16 v[18:33], v[70:73], v[218:221], v[18:33]
	ds_read_b128 v[70:73], v83 offset:57344
	v_exp_f32_e32 v152, v103
	v_cvt_pk_bf16_f32 v87, v149, v150
	v_exp_f32_e32 v153, v104
	s_waitcnt lgkmcnt(3)
	v_mfma_f32_32x32x16_bf16 v[2:17], v[66:69], v[218:221], v[2:17]
	ds_read_b128 v[66:69], v83 offset:61440
	v_exp_f32_e32 v154, v105
	v_cvt_pk_bf16_f32 v88, v151, v152
	v_cvt_pk_bf16_f32 v89, v153, v154
	s_waitcnt lgkmcnt(3)
	s_nop 0
	v_mfma_f32_32x32x16_bf16 v[50:65], v[78:81], v[86:89], v[50:65]
	ds_read_b128 v[78:81], v84 offset:49152
	v_exp_f32_e32 v155, v106
	v_exp_f32_e32 v156, v107
	v_exp_f32_e32 v157, v108
	s_waitcnt lgkmcnt(3)
	v_mfma_f32_32x32x16_bf16 v[34:49], v[74:77], v[86:89], v[34:49]
	ds_read_b128 v[74:77], v84 offset:53248
	v_cvt_pk_bf16_f32 v218, v155, v156
	v_exp_f32_e32 v158, v109
	v_exp_f32_e32 v110, v110
	s_waitcnt lgkmcnt(3)
	v_mfma_f32_32x32x16_bf16 v[18:33], v[70:73], v[86:89], v[18:33]
	ds_read_b128 v[70:73], v84 offset:57344
	v_exp_f32_e32 v111, v111
	v_cvt_pk_bf16_f32 v219, v157, v158
	v_exp_f32_e32 v112, v112
	s_waitcnt lgkmcnt(3)
	v_mfma_f32_32x32x16_bf16 v[2:17], v[66:69], v[86:89], v[2:17]
	ds_read_b128 v[66:69], v84 offset:61440
	v_exp_f32_e32 v113, v113
	v_cvt_pk_bf16_f32 v220, v110, v111
	v_cvt_pk_bf16_f32 v221, v112, v113
	s_waitcnt lgkmcnt(3)
	s_nop 0
	v_mfma_f32_32x32x16_bf16 v[50:65], v[78:81], v[218:221], v[50:65]
	s_waitcnt lgkmcnt(2)
	v_mfma_f32_32x32x16_bf16 v[34:49], v[74:77], v[218:221], v[34:49]
	s_waitcnt lgkmcnt(1)
	v_mfma_f32_32x32x16_bf16 v[18:33], v[70:73], v[218:221], v[18:33]
	s_waitcnt lgkmcnt(0)
	v_mfma_f32_32x32x16_bf16 v[2:17], v[66:69], v[218:221], v[2:17]
	v_add_u32_e32 v78, s1, v198
	v_add_u32_e32 v70, v78, v199
	s_waitcnt vmcnt(0)
	s_waitcnt vmcnt(0)
	s_barrier
	ds_read_b128 v[66:69], v70
	v_add_u32_e32 v79, v78, v200
	ds_read_b128 v[70:73], v70 offset:8192
	v_add_u32_e32 v80, v78, v201
	v_add_u32_e32 v78, v78, v202
	s_waitcnt lgkmcnt(1)
	v_mfma_f32_32x32x16_bf16 v[82:97], v[66:69], v[134:137], v[238:253]
	ds_read_b128 v[66:69], v79
	ds_read_b128 v[74:77], v80
	ds_read_b128 v[98:101], v79 offset:8192
	s_add_u32 s2, s2, 0x100
	s_addc_u32 s3, s3, 0
	s_add_u32 s4, s4, 0x20000
	s_addc_u32 s5, s5, 0
	s_cmp_eq_u32 s0, 0x410000
	s_waitcnt lgkmcnt(2)
	v_mfma_f32_32x32x16_bf16 v[82:97], v[66:69], v[130:133], v[82:97]
	v_add_f32_e32 v66, 0, v114
	v_add_f32_e32 v66, v115, v66
	v_add_f32_e32 v79, v116, v66
	ds_read_b128 v[102:105], v80 offset:8192
	ds_read_b128 v[66:69], v78
	ds_read_b128 v[106:109], v78 offset:8192
	s_waitcnt lgkmcnt(4)
	v_mfma_f32_32x32x16_bf16 v[82:97], v[74:77], v[142:145], v[82:97]
	v_add_f32_e32 v74, v117, v79
	v_add_f32_e32 v74, v118, v74
	v_add_f32_e32 v74, v119, v74
	v_add_f32_e32 v74, v120, v74
	v_add_f32_e32 v74, v121, v74
	v_add_f32_e32 v74, v122, v74
	v_add_f32_e32 v74, v123, v74
	s_waitcnt lgkmcnt(1)
	v_mfma_f32_32x32x16_bf16 v[82:97], v[66:69], v[138:141], v[82:97]
	v_add_f32_e32 v66, v124, v74
	v_add_f32_e32 v66, v125, v66
	v_add_f32_e32 v66, v126, v66
	v_add_f32_e32 v66, v127, v66
	v_add_f32_e32 v66, v128, v66
	v_add_f32_e32 v66, v129, v66
	v_add_f32_e32 v114, v147, v66
	v_mfma_f32_32x32x16_bf16 v[66:81], v[70:73], v[134:137], v[238:253]
	v_add_f32_e32 v114, v148, v114
	v_add_f32_e32 v114, v149, v114
	v_add_f32_e32 v114, v150, v114
	v_add_f32_e32 v114, v151, v114
	v_add_f32_e32 v114, v152, v114
	v_add_f32_e32 v114, v153, v114
	v_add_f32_e32 v114, v154, v114
	v_mfma_f32_32x32x16_bf16 v[66:81], v[98:101], v[130:133], v[66:81]
	v_add_f32_e32 v98, v155, v114
	v_add_f32_e32 v98, v156, v98
	v_add_f32_e32 v98, v157, v98
	v_add_f32_e32 v98, v158, v98
	v_add_f32_e32 v98, v110, v98
	v_add_f32_e32 v98, v111, v98
	v_add_f32_e32 v98, v112, v98
	v_mfma_f32_32x32x16_bf16 v[66:81], v[102:105], v[142:145], v[66:81]
	v_add_f32_e32 v98, v113, v98
	v_add_f32_e32 v213, v146, v98
	s_waitcnt lgkmcnt(0)
	v_mfma_f32_32x32x16_bf16 v[66:81], v[106:109], v[138:141], v[66:81]
	s_cbranch_scc1 .Lattn_unshift
